# indexer key buffer stored in MFMA-operand block order by the CIN epilogue so each index-scoring key load reads 1 KB contiguous (was 32 rows x 32 B)
# speedup vs baseline: 1.0183x; 1.0176x over previous
.LBB0_204:
	s_and_saveexec_b64 s[0:1], s[6:7]
	s_xor_b64 s[0:1], exec, s[0:1]
	s_cbranch_execz .LBB0_214
	v_lshlrev_b32_e32 v0, 7, v238
	v_lshlrev_b32_e32 v131, 3, v240
	v_add3_u32 v0, v241, v0, v131
	s_waitcnt lgkmcnt(1)
	v_mul_f32_e32 v131, v98, v134
	v_mul_f32_e32 v136, v99, v134
	v_cvt_pk_bf16_f32 v136, v131, v136
	v_mul_f32_e32 v131, v100, v134
	v_mul_f32_e32 v137, v101, v134
	v_cvt_pk_bf16_f32 v137, v131, v137
	v_lshlrev_b32_e32 v131, 4, v238
	v_and_b32_e32 v138, 0x70, v131
	v_add_u32_e32 v245, v0, v138
	ds_write_b64 v245, v[136:137]
	v_mul_f32_e32 v136, v102, v134
	v_mul_f32_e32 v137, v103, v134
	v_cvt_pk_bf16_f32 v136, v136, v137
	v_mul_f32_e32 v137, v104, v134
	v_mul_f32_e32 v138, v105, v134
	v_cvt_pk_bf16_f32 v137, v137, v138
	v_bitop3_b32 v138, v131, 16, v213 bitop3:0x6c
	v_add_u32_e32 v246, v0, v138
	ds_write_b64 v246, v[136:137]
	v_mul_f32_e32 v136, v106, v134
	v_mul_f32_e32 v137, v107, v134
	v_cvt_pk_bf16_f32 v136, v136, v137
	v_mul_f32_e32 v137, v108, v134
	v_mul_f32_e32 v138, v109, v134
	v_cvt_pk_bf16_f32 v137, v137, v138
	v_bitop3_b32 v138, v131, 32, v213 bitop3:0x6c
	v_add_u32_e32 v247, v0, v138
	ds_write_b64 v247, v[136:137]
	v_mul_f32_e32 v136, v110, v134
	v_mul_f32_e32 v137, v111, v134
	v_cvt_pk_bf16_f32 v136, v136, v137
	v_mul_f32_e32 v137, v112, v134
	v_mul_f32_e32 v138, v113, v134
	v_cvt_pk_bf16_f32 v137, v137, v138
	v_bitop3_b32 v138, v131, 48, v213 bitop3:0x6c
	v_add_u32_e32 v248, v0, v138
	ds_write_b64 v248, v[136:137]
	v_mul_f32_e32 v136, v114, v134
	v_mul_f32_e32 v137, v115, v134
	v_cvt_pk_bf16_f32 v136, v136, v137
	v_mul_f32_e32 v137, v116, v134
	v_mul_f32_e32 v138, v117, v134
	v_cvt_pk_bf16_f32 v137, v137, v138
	v_bitop3_b32 v138, v131, 64, v213 bitop3:0x6c
	v_add_u32_e32 v249, v0, v138
	ds_write_b64 v249, v[136:137]
	v_mul_f32_e32 v136, v118, v134
	v_mul_f32_e32 v137, v119, v134
	v_cvt_pk_bf16_f32 v136, v136, v137
	v_mul_f32_e32 v137, v120, v134
	v_mul_f32_e32 v138, v121, v134
	v_cvt_pk_bf16_f32 v137, v137, v138
	v_bitop3_b32 v138, v131, s70, v213 bitop3:0x6c
	v_add_u32_e32 v215, v0, v138
	ds_write_b64 v215, v[136:137]
	v_mul_f32_e32 v136, v122, v134
	v_mul_f32_e32 v137, v123, v134
	v_cvt_pk_bf16_f32 v136, v136, v137
	v_mul_f32_e32 v137, v124, v134
	v_mul_f32_e32 v138, v125, v134
	v_cvt_pk_bf16_f32 v137, v137, v138
	v_bitop3_b32 v138, v131, s63, v213 bitop3:0x6c
	v_add_u32_e32 v211, v0, v138
	ds_write_b64 v211, v[136:137]
	v_mul_f32_e32 v136, v126, v134
	v_mul_f32_e32 v137, v127, v134
	v_bitop3_b32 v131, v131, s55, v131 bitop3:0xc
	v_cvt_pk_bf16_f32 v136, v136, v137
	v_mul_f32_e32 v137, v128, v134
	v_mul_f32_e32 v138, v129, v134
	v_add_u32_e32 v209, v0, v131
	v_mul_f32_e32 v0, v66, v135
	v_mul_f32_e32 v131, v67, v135
	v_cvt_pk_bf16_f32 v137, v137, v138
	v_cvt_pk_bf16_f32 v138, v0, v131
	v_mul_f32_e32 v0, v68, v135
	v_mul_f32_e32 v131, v69, v135
	v_cvt_pk_bf16_f32 v139, v0, v131
	v_mul_f32_e32 v0, v70, v135
	v_mul_f32_e32 v131, v71, v135
	ds_write_b64 v245, v[138:139] offset:4096
	v_cvt_pk_bf16_f32 v138, v0, v131
	v_mul_f32_e32 v0, v72, v135
	v_mul_f32_e32 v131, v73, v135
	v_cvt_pk_bf16_f32 v139, v0, v131
	v_mul_f32_e32 v0, v74, v135
	v_mul_f32_e32 v131, v75, v135
	ds_write_b64 v246, v[138:139] offset:4096
	v_cvt_pk_bf16_f32 v138, v0, v131
	v_mul_f32_e32 v0, v76, v135
	v_mul_f32_e32 v131, v77, v135
	v_cvt_pk_bf16_f32 v139, v0, v131
	v_mul_f32_e32 v0, v78, v135
	v_mul_f32_e32 v131, v79, v135
	ds_write_b64 v247, v[138:139] offset:4096
	v_cvt_pk_bf16_f32 v138, v0, v131
	v_mul_f32_e32 v0, v80, v135
	v_mul_f32_e32 v131, v81, v135
	v_cvt_pk_bf16_f32 v139, v0, v131
	v_mul_f32_e32 v0, v82, v135
	v_mul_f32_e32 v131, v83, v135
	ds_write_b64 v248, v[138:139] offset:4096
	v_cvt_pk_bf16_f32 v138, v0, v131
	v_mul_f32_e32 v0, v84, v135
	v_mul_f32_e32 v131, v85, v135
	v_cvt_pk_bf16_f32 v139, v0, v131
	v_mul_f32_e32 v0, v86, v135
	v_mul_f32_e32 v131, v87, v135
	ds_write_b64 v249, v[138:139] offset:4096
	v_cvt_pk_bf16_f32 v138, v0, v131
	v_mul_f32_e32 v0, v88, v135
	v_mul_f32_e32 v131, v89, v135
	v_cvt_pk_bf16_f32 v139, v0, v131
	v_mul_f32_e32 v0, v90, v135
	v_mul_f32_e32 v131, v91, v135
	ds_write_b64 v215, v[138:139] offset:4096
	v_cvt_pk_bf16_f32 v138, v0, v131
	v_mul_f32_e32 v0, v92, v135
	v_mul_f32_e32 v131, v93, v135
	v_cvt_pk_bf16_f32 v139, v0, v131
	v_mul_f32_e32 v0, v94, v135
	v_mul_f32_e32 v131, v95, v135
	ds_write_b64 v211, v[138:139] offset:4096
	v_cvt_pk_bf16_f32 v138, v0, v131
	v_mul_f32_e32 v0, v96, v135
	v_mul_f32_e32 v131, v97, v135
	v_cvt_pk_bf16_f32 v139, v0, v131
	v_ashrrev_i32_e32 v131, 31, v130
	s_mov_b64 s[6:7], -1
	s_and_b64 vcc, exec, s[2:3]
	ds_write2st64_b64 v209, v[136:137], v[138:139] offset1:8
	s_cbranch_vccz .LBB0_207
	v_readlane_b32 s6, v252, 27
	v_lshlrev_b64 v[136:137], 7, v[130:131]
	v_readlane_b32 s7, v252, 28
	s_nop 1
	v_lshl_add_u64 v[172:173], s[6:7], 0, v[136:137]
	v_and_b32_e32 v136, 7, v239
	v_lshrrev_b32_e32 v137, 1, v136
	v_lshlrev_b32_e32 v137, 10, v137
	v_and_b32_e32 v138, 1, v136
	v_lshl_or_b32 v137, v138, 9, v137
	v_lshlrev_b32_e32 v136, 4, v136
	v_sub_u32_e32 v136, v137, v136
	v_mov_b32_e32 v137, 0
	v_lshl_add_u64 v[172:173], v[172:173], 0, v[136:137]
	s_mov_b64 s[6:7], 0
.LBB0_207:
	v_ashrrev_i32_e32 v178, 3, v239
	v_add_u32_e32 v180, 8, v178
	v_add_u32_e32 v184, 16, v178
	v_add_u32_e32 v186, 24, v178
	v_add_u32_e32 v188, 32, v178
	v_add_u32_e32 v190, 40, v178
	v_add_u32_e32 v194, 48, v178
	v_add_u32_e32 v196, 56, v178
	v_ashrrev_i32_e32 v179, 31, v178
	v_ashrrev_i32_e32 v181, 31, v180
	v_ashrrev_i32_e32 v185, 31, v184
	v_ashrrev_i32_e32 v187, 31, v186
	v_ashrrev_i32_e32 v189, 31, v188
	v_ashrrev_i32_e32 v191, 31, v190
	v_ashrrev_i32_e32 v195, 31, v194
	v_ashrrev_i32_e32 v197, 31, v196
	v_lshlrev_b64 v[150:151], 4, v[178:179]
	v_lshlrev_b64 v[148:149], 4, v[180:181]
	v_lshlrev_b64 v[146:147], 4, v[184:185]
	v_lshlrev_b64 v[144:145], 4, v[186:187]
	v_lshlrev_b64 v[142:143], 4, v[188:189]
	v_add_u32_e32 v142, 0xe00, v142
	v_lshlrev_b64 v[140:141], 4, v[190:191]
	v_add_u32_e32 v140, 0xe00, v140
	v_lshlrev_b64 v[138:139], 4, v[194:195]
	v_add_u32_e32 v138, 0xe00, v138
	v_lshlrev_b64 v[136:137], 4, v[196:197]
	v_add_u32_e32 v136, 0xe00, v136
	v_lshlrev_b32_e32 v168, 6, v242
	s_lshl_b32 s8, s10, 7
	v_ashrrev_i32_e32 v169, 31, v168
	v_lshlrev_b64 v[152:153], 10, v[178:179]
	v_lshlrev_b64 v[154:155], 10, v[180:181]
	v_lshlrev_b64 v[156:157], 10, v[184:185]
	v_lshlrev_b64 v[158:159], 10, v[186:187]
	v_lshlrev_b64 v[160:161], 10, v[188:189]
	v_lshlrev_b64 v[162:163], 10, v[190:191]
	v_lshlrev_b64 v[164:165], 10, v[194:195]
	v_lshlrev_b64 v[166:167], 10, v[196:197]
	s_andn2_b64 vcc, exec, s[6:7]
	v_mov_b64_e32 v[202:203], v[150:151]
	v_mov_b64_e32 v[200:201], v[148:149]
	v_mov_b64_e32 v[198:199], v[146:147]
	v_mov_b64_e32 v[192:193], v[144:145]
	v_mov_b64_e32 v[182:183], v[142:143]
	v_mov_b64_e32 v[176:177], v[140:141]
	v_mov_b64_e32 v[174:175], v[138:139]
	v_mov_b64_e32 v[170:171], v[136:137]
	s_cbranch_vccnz .LBB0_209
	v_readlane_b32 s6, v252, 39
	v_lshlrev_b64 v[170:171], 10, v[130:131]
	v_readlane_b32 s7, v252, 40
	s_lshl_b32 s82, s8, 1
	v_mov_b64_e32 v[202:203], v[152:153]
	v_lshl_add_u64 v[170:171], s[6:7], 0, v[170:171]
	v_lshl_add_u64 v[170:171], v[170:171], 0, s[82:83]
	s_movk_i32 s6, 0xf400
	v_lshl_add_u64 v[170:171], v[168:169], 1, v[170:171]
	s_mov_b32 s7, -1
	v_lshl_add_u64 v[172:173], v[170:171], 0, s[6:7]
	v_mov_b64_e32 v[200:201], v[154:155]
	v_mov_b64_e32 v[198:199], v[156:157]
	v_mov_b64_e32 v[192:193], v[158:159]
	v_mov_b64_e32 v[182:183], v[160:161]
	v_mov_b64_e32 v[176:177], v[162:163]
	v_mov_b64_e32 v[174:175], v[164:165]
	v_mov_b64_e32 v[170:171], v[166:167]
.LBB0_209:
	v_xor_b32_e32 v0, v178, v239
	v_lshlrev_b32_e32 v0, 4, v0
	v_and_b32_e32 v0, 0x70, v0
	v_add_u32_e32 v131, v241, v0
	v_lshlrev_b32_e32 v178, 7, v178
	v_add_u32_e32 v185, v131, v178
	v_lshlrev_b32_e32 v0, 3, v239
	v_lshlrev_b32_e32 v187, 7, v180
	ds_read_b128 v[178:181], v185
	v_and_b32_e32 v0, 56, v0
	v_lshlrev_b32_e32 v0, 1, v0
	v_lshlrev_b32_e32 v208, 7, v190
	v_lshl_add_u64 v[190:191], v[172:173], 0, v[0:1]
	v_lshl_add_u64 v[172:173], v[190:191], 0, v[202:203]
	s_waitcnt lgkmcnt(0)
	global_store_dwordx4 v[172:173], v[178:181], off
	v_lshlrev_b32_e32 v195, 7, v186
	v_lshlrev_b32_e32 v197, 7, v188
	v_add_u32_e32 v181, v131, v187
	ds_read_b128 v[186:189], v181
	v_lshlrev_b32_e32 v184, 7, v184
	v_lshl_add_u64 v[172:173], v[190:191], 0, v[200:201]
	v_add_u32_e32 v184, v131, v184
	v_add_u32_e32 v180, v131, v195
	s_waitcnt lgkmcnt(0)
	global_store_dwordx4 v[172:173], v[186:189], off
	ds_read_b128 v[186:189], v184
	v_lshl_add_u64 v[172:173], v[190:191], 0, v[198:199]
	v_add_u32_e32 v179, v131, v197
	v_add_u32_e32 v178, v131, v208
	v_lshlrev_b32_e32 v194, 7, v194
	s_waitcnt lgkmcnt(0)
	global_store_dwordx4 v[172:173], v[186:189], off
	ds_read_b128 v[186:189], v180
	v_lshl_add_u64 v[172:173], v[190:191], 0, v[192:193]
	v_lshlrev_b32_e32 v196, 7, v196
	v_lshl_add_u64 v[170:171], v[190:191], 0, v[170:171]
	s_mov_b64 s[6:7], -1
	s_waitcnt lgkmcnt(0)
	global_store_dwordx4 v[172:173], v[186:189], off
	ds_read_b128 v[186:189], v179
	v_lshl_add_u64 v[172:173], v[190:191], 0, v[182:183]
	s_andn2_b64 vcc, exec, s[2:3]
	s_waitcnt lgkmcnt(0)
	global_store_dwordx4 v[172:173], v[186:189], off
	ds_read_b128 v[186:189], v178
	v_lshl_add_u64 v[172:173], v[190:191], 0, v[176:177]
	v_add_u32_e32 v176, v131, v194
	v_add_u32_e32 v131, v131, v196
	s_waitcnt lgkmcnt(0)
	global_store_dwordx4 v[172:173], v[186:189], off
	ds_read_b128 v[186:189], v176
	v_lshl_add_u64 v[172:173], v[190:191], 0, v[174:175]
	s_waitcnt lgkmcnt(0)
	global_store_dwordx4 v[172:173], v[186:189], off
	ds_read_b128 v[172:175], v131
	s_waitcnt lgkmcnt(0)
	global_store_dwordx4 v[170:171], v[172:175], off
	v_mul_f32_e32 v170, v34, v132
	v_mul_f32_e32 v171, v35, v132
	v_cvt_pk_bf16_f32 v170, v170, v171
	v_mul_f32_e32 v171, v36, v132
	v_mul_f32_e32 v172, v37, v132
	v_cvt_pk_bf16_f32 v171, v171, v172
	ds_write_b64 v245, v[170:171]
	v_mul_f32_e32 v170, v38, v132
	v_mul_f32_e32 v171, v39, v132
	v_cvt_pk_bf16_f32 v170, v170, v171
	v_mul_f32_e32 v171, v40, v132
	v_mul_f32_e32 v172, v41, v132
	v_cvt_pk_bf16_f32 v171, v171, v172
	ds_write_b64 v246, v[170:171]
	v_mul_f32_e32 v170, v42, v132
	v_mul_f32_e32 v171, v43, v132
	v_cvt_pk_bf16_f32 v170, v170, v171
	v_mul_f32_e32 v171, v44, v132
	v_mul_f32_e32 v172, v45, v132
	v_cvt_pk_bf16_f32 v171, v171, v172
	ds_write_b64 v247, v[170:171]
	v_mul_f32_e32 v170, v46, v132
	v_mul_f32_e32 v171, v47, v132
	v_cvt_pk_bf16_f32 v170, v170, v171
	v_mul_f32_e32 v171, v48, v132
	v_mul_f32_e32 v172, v49, v132
	v_cvt_pk_bf16_f32 v171, v171, v172
	ds_write_b64 v248, v[170:171]
	v_mul_f32_e32 v170, v50, v132
	v_mul_f32_e32 v171, v51, v132
	v_cvt_pk_bf16_f32 v170, v170, v171
	v_mul_f32_e32 v171, v52, v132
	v_mul_f32_e32 v172, v53, v132
	v_cvt_pk_bf16_f32 v171, v171, v172
	ds_write_b64 v249, v[170:171]
	v_mul_f32_e32 v170, v54, v132
	v_mul_f32_e32 v171, v55, v132
	v_cvt_pk_bf16_f32 v170, v170, v171
	v_mul_f32_e32 v171, v56, v132
	v_mul_f32_e32 v172, v57, v132
	v_cvt_pk_bf16_f32 v171, v171, v172
	ds_write_b64 v215, v[170:171]
	v_mul_f32_e32 v170, v58, v132
	v_mul_f32_e32 v171, v59, v132
	v_cvt_pk_bf16_f32 v170, v170, v171
	v_mul_f32_e32 v171, v60, v132
	v_mul_f32_e32 v172, v61, v132
	v_cvt_pk_bf16_f32 v171, v171, v172
	ds_write_b64 v211, v[170:171]
	v_mul_f32_e32 v170, v62, v132
	v_mul_f32_e32 v171, v63, v132
	v_cvt_pk_bf16_f32 v170, v170, v171
	v_mul_f32_e32 v171, v64, v132
	v_mul_f32_e32 v172, v65, v132
	v_cvt_pk_bf16_f32 v171, v171, v172
	v_mul_f32_e32 v172, v2, v133
	v_mul_f32_e32 v173, v3, v133
	v_cvt_pk_bf16_f32 v172, v172, v173
	v_mul_f32_e32 v173, v4, v133
	v_mul_f32_e32 v174, v5, v133
	v_cvt_pk_bf16_f32 v173, v173, v174
	ds_write_b64 v245, v[172:173] offset:4096
	v_mul_f32_e32 v172, v6, v133
	v_mul_f32_e32 v173, v7, v133
	v_cvt_pk_bf16_f32 v172, v172, v173
	v_mul_f32_e32 v173, v8, v133
	v_mul_f32_e32 v174, v9, v133
	v_cvt_pk_bf16_f32 v173, v173, v174
	ds_write_b64 v246, v[172:173] offset:4096
	v_mul_f32_e32 v172, v10, v133
	v_mul_f32_e32 v173, v11, v133
	v_cvt_pk_bf16_f32 v172, v172, v173
	v_mul_f32_e32 v173, v12, v133
	v_mul_f32_e32 v174, v13, v133
	v_cvt_pk_bf16_f32 v173, v173, v174
	ds_write_b64 v247, v[172:173] offset:4096
	v_mul_f32_e32 v172, v14, v133
	v_mul_f32_e32 v173, v15, v133
	v_cvt_pk_bf16_f32 v172, v172, v173
	v_mul_f32_e32 v173, v16, v133
	v_mul_f32_e32 v174, v17, v133
	v_cvt_pk_bf16_f32 v173, v173, v174
	ds_write_b64 v248, v[172:173] offset:4096
	v_mul_f32_e32 v172, v18, v133
	v_mul_f32_e32 v173, v19, v133
	v_cvt_pk_bf16_f32 v172, v172, v173
	v_mul_f32_e32 v173, v20, v133
	v_mul_f32_e32 v174, v21, v133
	v_cvt_pk_bf16_f32 v173, v173, v174
	ds_write_b64 v249, v[172:173] offset:4096
	v_mul_f32_e32 v172, v22, v133
	v_mul_f32_e32 v173, v23, v133
	v_cvt_pk_bf16_f32 v172, v172, v173
	v_mul_f32_e32 v173, v24, v133
	v_mul_f32_e32 v174, v25, v133
	v_cvt_pk_bf16_f32 v173, v173, v174
	ds_write_b64 v215, v[172:173] offset:4096
	v_mul_f32_e32 v172, v26, v133
	v_mul_f32_e32 v173, v27, v133
	v_cvt_pk_bf16_f32 v172, v172, v173
	v_mul_f32_e32 v173, v28, v133
	v_mul_f32_e32 v174, v29, v133
	v_cvt_pk_bf16_f32 v173, v173, v174
	ds_write_b64 v211, v[172:173] offset:4096
	v_mul_f32_e32 v172, v30, v133
	v_mul_f32_e32 v173, v31, v133
	v_cvt_pk_bf16_f32 v172, v172, v173
	v_mul_f32_e32 v173, v32, v133
	v_mul_f32_e32 v174, v33, v133
	v_cvt_pk_bf16_f32 v173, v173, v174
	ds_write2st64_b64 v209, v[170:171], v[172:173] offset1:8
	v_or_b32_e32 v170, 64, v130
	v_ashrrev_i32_e32 v171, 31, v170
	s_cbranch_vccnz .LBB0_211
	v_readlane_b32 s2, v252, 27
	v_lshlrev_b64 v[172:173], 7, v[170:171]
	v_readlane_b32 s3, v252, 28
	s_mov_b64 s[6:7], 0
	s_nop 0
	v_lshl_add_u64 v[172:173], s[2:3], 0, v[172:173]
	v_and_b32_e32 v170, 7, v239
	v_lshrrev_b32_e32 v171, 1, v170
	v_lshlrev_b32_e32 v171, 10, v171
	v_and_b32_e32 v174, 1, v170
	v_lshl_or_b32 v171, v174, 9, v171
	v_lshlrev_b32_e32 v170, 4, v170
	v_sub_u32_e32 v170, v171, v170
	v_mov_b32_e32 v171, 0
	v_lshl_add_u64 v[172:173], v[172:173], 0, v[170:171]

.LBB0_288:
	v_writelane_b32 v251, s2, 58
	s_and_b64 s[0:1], s[2:3], exec
	s_cselect_b32 s0, s7, s6
	v_writelane_b32 v251, s3, 59
	s_ashr_i32 s4, s0, 4
	s_bfe_u32 s2, s0, 0x20002
	s_lshl_b32 s1, s2, 12
	s_lshl_b32 s3, s4, 6
	s_lshl_b32 s0, s0, 4
	s_add_i32 s1, s1, s3
	s_and_b32 s0, s0, 48
	s_or_b32 s0, s1, s0
	v_mov_b32_e32 v188, v205
	v_writelane_b32 v251, s0, 60
	s_cmp_gt_i32 s4, 3
	s_mov_b64 s[0:1], -1
	s_cbranch_scc0 .LBB0_985
	v_and_b32_e32 v0, 3, v188
	v_lshrrev_b32_e32 v2, 1, v188
	v_and_or_b32 v0, v2, 4, v0
	v_readlane_b32 s0, v252, 39
	v_bfe_u32 v5, v188, 5, 1
	v_bfe_u32 v3, v188, 4, 1
	v_lshlrev_b32_e32 v0, 7, v0
	v_readlane_b32 s1, v252, 40
	v_ashrrev_i32_e32 v189, 6, v188
	s_lshl_b32 s3, s4, 1
	v_and_or_b32 v191, v2, 2, v3
	v_lshl_add_u64 v[2:3], s[0:1], 0, v[0:1]
	v_lshlrev_b32_e32 v0, 4, v5
	v_lshl_add_u64 v[174:175], v[2:3], 0, v[0:1]
	v_sub_u32_e32 v2, s3, v189
	s_mov_b32 s6, s4
	s_add_i32 s94, s3, 2
	v_add_u32_e32 v2, 5, v2
	s_lshl_b32 s0, s2, 19
	v_readlane_b32 s4, v252, 27
	v_ashrrev_i32_e32 v193, 2, v2
	v_readlane_b32 s5, v252, 28
	s_add_u32 s0, s4, s0
	s_addc_u32 s1, s5, 0
	s_or_b32 s95, s3, 1
	v_cmp_lt_i32_e64 s[2:3], 0, v193
	s_cmp_gt_u32 s6, 15
	v_and_b32_e32 v4, 63, v188
	v_writelane_b32 v251, s2, 61
	v_lshlrev_b32_e32 v0, 9, v5
	v_lshl_add_u64 v[176:177], s[0:1], 0, v[0:1]
	v_lshlrev_b32_e32 v0, 14, v189
	v_writelane_b32 v251, s3, 62
	s_cselect_b64 s[2:3], -1, 0
	v_writelane_b32 v251, s2, 63
	s_cmp_gt_u32 s6, 31
	v_lshlrev_b32_e32 v2, 2, v4
	v_writelane_b32 v253, s3, 0
	s_cselect_b64 s[2:3], -1, 0
	v_writelane_b32 v253, s2, 1
	s_cmp_gt_u32 s6, 47
	v_add3_u32 v194, s80, v0, v2
	v_writelane_b32 v253, s3, 2
	s_cselect_b64 s[2:3], -1, 0
	v_writelane_b32 v253, s2, 3
	s_cmp_eq_u32 s6, 48
	v_add_u32_e32 v0, 12, v189
	v_writelane_b32 v253, s3, 4
	s_cselect_b64 s[2:3], -1, 0
	v_writelane_b32 v253, s2, 5
	s_cmp_lt_u32 s6, 50
	v_and_b32_e32 v190, 31, v188
	v_writelane_b32 v253, s3, 6
	s_cselect_b64 s[2:3], -1, 0
	v_writelane_b32 v253, s2, 7
	s_cmp_lt_u32 s6, 51
	v_lshlrev_b64 v[2:3], v188, -1
	v_writelane_b32 v253, s3, 8
	s_cselect_b64 s[2:3], -1, 0
	v_writelane_b32 v253, s2, 9
	s_cmp_lt_u32 s6, 52
	v_min_i32_e32 v0, s95, v0
	v_writelane_b32 v253, s3, 10
	s_cselect_b64 s[2:3], -1, 0
	v_writelane_b32 v253, s2, 11
	s_cmp_lt_u32 s6, 53
	v_not_b32_e32 v178, v2
	v_writelane_b32 v253, s3, 12
	s_cselect_b64 s[2:3], -1, 0
	v_writelane_b32 v253, s2, 13
	s_cmp_lt_u32 s6, 54
	v_lshl_or_b32 v2, v0, 8, v190
	v_writelane_b32 v253, s3, 14
	s_cselect_b64 s[2:3], -1, 0
	v_writelane_b32 v253, s2, 15
	s_cmp_lt_u32 s6, 55
	v_not_b32_e32 v179, v3
	v_writelane_b32 v253, s3, 16
	s_cselect_b64 s[2:3], -1, 0
	v_writelane_b32 v253, s2, 17
	s_cmp_lt_u32 s6, 56
	v_ashrrev_i32_e32 v3, 31, v2
	v_writelane_b32 v253, s3, 18
	s_cselect_b64 s[2:3], -1, 0
	v_writelane_b32 v253, s2, 19
	s_cmp_lt_u32 s6, 57
	v_add_u32_e32 v0, 8, v189
	v_writelane_b32 v253, s3, 20
	s_cselect_b64 s[2:3], -1, 0
	v_writelane_b32 v253, s2, 21
	s_cmp_lt_u32 s6, 58
	v_lshlrev_b64 v[2:3], 4, v[2:3]
	v_writelane_b32 v253, s3, 22
	s_cselect_b64 s[2:3], -1, 0
	v_writelane_b32 v253, s2, 23
	s_cmp_lt_u32 s6, 59
	v_min_i32_e32 v0, s95, v0
	v_writelane_b32 v253, s3, 24
	s_cselect_b64 s[2:3], -1, 0
	v_writelane_b32 v253, s2, 25
	s_cmp_lt_u32 s6, 60
	v_lshl_add_u64 v[180:181], v[176:177], 0, v[2:3]
	v_writelane_b32 v253, s3, 26
	s_cselect_b64 s[2:3], -1, 0
	v_writelane_b32 v253, s2, 27
	s_cmp_lt_u32 s6, 61
	v_lshl_or_b32 v2, v0, 8, v190
	v_writelane_b32 v253, s3, 28
	s_cselect_b64 s[2:3], -1, 0
	v_writelane_b32 v253, s2, 29
	s_cmp_lt_u32 s6, 62
	v_ashrrev_i32_e32 v3, 31, v2
	v_writelane_b32 v253, s3, 30
	s_cselect_b64 s[2:3], -1, 0
	v_writelane_b32 v253, s2, 31
	s_cmp_lt_u32 s6, 63
	v_add_u32_e32 v0, 4, v189
	v_writelane_b32 v253, s3, 32
	s_cselect_b64 s[2:3], -1, 0
	v_writelane_b32 v253, s2, 33
	s_cmp_eq_u32 s6, 32
	v_lshlrev_b64 v[2:3], 4, v[2:3]
	v_writelane_b32 v253, s3, 34
	s_cselect_b64 s[2:3], -1, 0
	v_writelane_b32 v253, s2, 35
	s_cmp_lt_u32 s6, 34
	v_min_i32_e32 v0, s95, v0
	v_writelane_b32 v253, s3, 36
	s_cselect_b64 s[2:3], -1, 0
	v_writelane_b32 v253, s2, 37
	s_cmp_lt_u32 s6, 35
	v_lshl_add_u64 v[182:183], v[176:177], 0, v[2:3]
	v_writelane_b32 v253, s3, 38
	s_cselect_b64 s[2:3], -1, 0
	v_writelane_b32 v253, s2, 39
	s_cmp_lt_u32 s6, 36
	v_lshl_or_b32 v2, v0, 8, v190
	v_writelane_b32 v253, s3, 40
	s_cselect_b64 s[2:3], -1, 0
	v_writelane_b32 v253, s2, 41
	s_cmp_lt_u32 s6, 37
	v_ashrrev_i32_e32 v3, 31, v2
	v_writelane_b32 v253, s3, 42
	s_cselect_b64 s[2:3], -1, 0
	v_writelane_b32 v253, s2, 43
	s_cmp_lt_u32 s6, 38
	v_lshlrev_b64 v[2:3], 4, v[2:3]
	v_writelane_b32 v253, s3, 44
	s_cselect_b64 s[2:3], -1, 0
	v_writelane_b32 v253, s2, 45
	s_cmp_lt_u32 s6, 39
	v_min_i32_e32 v0, s95, v189
	v_writelane_b32 v253, s3, 46
	s_cselect_b64 s[2:3], -1, 0
	v_writelane_b32 v253, s2, 47
	s_cmp_lt_u32 s6, 40
	v_lshl_add_u64 v[184:185], v[176:177], 0, v[2:3]
	v_writelane_b32 v253, s3, 48
	s_cselect_b64 s[2:3], -1, 0
	v_writelane_b32 v253, s2, 49
	s_cmp_lt_u32 s6, 41
	v_lshl_or_b32 v2, v0, 8, v190
	v_writelane_b32 v253, s3, 50
	s_cselect_b64 s[2:3], -1, 0
	v_writelane_b32 v253, s2, 51
	s_cmp_lt_u32 s6, 42
	v_lshlrev_b32_e32 v0, 7, v189
	v_writelane_b32 v253, s3, 52
	s_cselect_b64 s[2:3], -1, 0
	v_writelane_b32 v253, s2, 53
	s_cmp_lt_u32 s6, 43
	v_cmp_eq_u32_e64 s[74:75], 0, v4
	v_writelane_b32 v253, s3, 54
	s_cselect_b64 s[2:3], -1, 0
	v_writelane_b32 v253, s2, 55
	s_cmp_lt_u32 s6, 44
	v_ashrrev_i32_e32 v3, 31, v2
	v_writelane_b32 v253, s3, 56
	s_cselect_b64 s[2:3], -1, 0
	v_writelane_b32 v253, s2, 57
	s_cmp_lt_u32 s6, 45
	v_lshl_add_u32 v0, v5, 15, v0
	v_writelane_b32 v253, s3, 58
	s_cselect_b64 s[2:3], -1, 0
	v_writelane_b32 v253, s2, 59
	s_cmp_lt_u32 s6, 46
	v_lshlrev_b64 v[2:3], 4, v[2:3]
	v_writelane_b32 v253, s3, 60
	s_cselect_b64 s[2:3], -1, 0
	v_writelane_b32 v253, s2, 61
	s_cmp_eq_u32 s6, 47
	v_lshl_or_b32 v0, v190, 2, v0
	v_writelane_b32 v253, s3, 62
	s_cselect_b64 s[2:3], -1, 0
	v_writelane_b32 v253, s2, 63
	s_cmp_eq_u32 s6, 16
	v_lshlrev_b32_e32 v192, 1, v5
	v_writelane_b32 v254, s3, 0
	s_cselect_b64 s[2:3], -1, 0
	v_writelane_b32 v254, s2, 1
	s_cmp_lt_u32 s6, 18
	s_mov_b32 s0, 0
	v_writelane_b32 v254, s3, 2
	s_cselect_b64 s[2:3], -1, 0
	v_writelane_b32 v254, s2, 3
	s_cmp_lt_u32 s6, 19
	v_lshl_add_u64 v[186:187], v[176:177], 0, v[2:3]
	v_writelane_b32 v254, s3, 4
	s_cselect_b64 s[2:3], -1, 0
	v_writelane_b32 v254, s2, 5
	s_cmp_lt_u32 s6, 20
	v_add_u32_e32 v195, s80, v0
	v_writelane_b32 v254, s3, 6
	s_cselect_b64 s[2:3], -1, 0
	v_writelane_b32 v254, s2, 7
	s_cmp_lt_u32 s6, 21
	s_nop 0
	v_writelane_b32 v254, s3, 8
	s_cselect_b64 s[2:3], -1, 0
	v_writelane_b32 v254, s2, 9
	s_cmp_lt_u32 s6, 22
	s_nop 0
	v_writelane_b32 v254, s3, 10
	s_cselect_b64 s[2:3], -1, 0
	v_writelane_b32 v254, s2, 11
	s_cmp_lt_u32 s6, 23
	s_nop 0
	v_writelane_b32 v254, s3, 12
	s_cselect_b64 s[2:3], -1, 0
	v_writelane_b32 v254, s2, 13
	s_cmp_lt_u32 s6, 24
	s_nop 0
	v_writelane_b32 v254, s3, 14
	s_cselect_b64 s[2:3], -1, 0
	v_writelane_b32 v254, s2, 15
	s_cmp_lt_u32 s6, 25
	s_nop 0
	v_writelane_b32 v254, s3, 16
	s_cselect_b64 s[2:3], -1, 0
	v_writelane_b32 v254, s2, 17
	s_cmp_lt_u32 s6, 26
	s_nop 0
	v_writelane_b32 v254, s3, 18
	s_cselect_b64 s[2:3], -1, 0
	v_writelane_b32 v254, s2, 19
	s_cmp_lt_u32 s6, 27
	s_nop 0
	v_writelane_b32 v254, s3, 20
	s_cselect_b64 s[2:3], -1, 0
	v_writelane_b32 v254, s2, 21
	s_cmp_lt_u32 s6, 28
	s_nop 0
	v_writelane_b32 v254, s3, 22
	s_cselect_b64 s[2:3], -1, 0
	v_writelane_b32 v254, s2, 23
	s_cmp_lt_u32 s6, 29
	s_nop 0
	v_writelane_b32 v254, s3, 24
	s_cselect_b64 s[2:3], -1, 0
	v_writelane_b32 v254, s2, 25
	s_cmp_lt_u32 s6, 30
	s_nop 0
	v_writelane_b32 v254, s3, 26
	s_cselect_b64 s[2:3], -1, 0
	v_writelane_b32 v254, s2, 27
	s_cmp_eq_u32 s6, 31
	s_nop 0
	v_writelane_b32 v254, s3, 28
	s_cselect_b64 s[2:3], -1, 0
	v_writelane_b32 v254, s2, 29
	s_cmp_eq_u32 s6, 4
	s_nop 0
	v_writelane_b32 v254, s3, 30
	s_cselect_b64 s[2:3], -1, 0
	v_writelane_b32 v254, s2, 31
	s_cmp_lt_u32 s6, 6
	s_nop 0
	v_writelane_b32 v254, s3, 32
	s_cselect_b64 s[2:3], -1, 0
	v_writelane_b32 v254, s2, 33
	s_cmp_lt_u32 s6, 7
	s_nop 0
	v_writelane_b32 v254, s3, 34
	s_cselect_b64 s[2:3], -1, 0
	v_writelane_b32 v254, s2, 35
	s_cmp_lt_u32 s6, 8
	s_nop 0
	v_writelane_b32 v254, s3, 36
	s_cselect_b64 s[2:3], -1, 0
	v_writelane_b32 v254, s2, 37
	s_cmp_lt_u32 s6, 9
	s_nop 0
	v_writelane_b32 v254, s3, 38
	s_cselect_b64 s[2:3], -1, 0
	v_writelane_b32 v254, s2, 39
	s_cmp_lt_u32 s6, 10
	s_nop 0
	v_writelane_b32 v254, s3, 40
	s_cselect_b64 s[2:3], -1, 0
	v_writelane_b32 v254, s2, 41
	s_cmp_lt_u32 s6, 11
	s_nop 0
	v_writelane_b32 v254, s3, 42
	s_cselect_b64 s[2:3], -1, 0
	v_writelane_b32 v254, s2, 43
	s_cmp_lt_u32 s6, 12
	s_nop 0
	v_writelane_b32 v254, s3, 44
	s_cselect_b64 s[2:3], -1, 0
	v_writelane_b32 v254, s2, 45
	s_cmp_lt_u32 s6, 13
	s_nop 0
	v_writelane_b32 v254, s3, 46
	s_cselect_b64 s[2:3], -1, 0
	v_writelane_b32 v254, s2, 47
	s_cmp_lt_u32 s6, 14
	s_nop 0
	v_writelane_b32 v254, s3, 48
	s_cselect_b64 s[2:3], -1, 0
	v_writelane_b32 v254, s2, 49
	s_cmp_eq_u32 s6, 15
	s_nop 0
	v_writelane_b32 v254, s3, 50
	v_writelane_b32 v254, s6, 51
	s_cselect_b64 s[2:3], -1, 0
	v_writelane_b32 v254, s2, 52
	s_nop 1
	v_writelane_b32 v254, s3, 53
	v_writelane_b32 v254, s8, 54
	v_writelane_b32 v254, s8, 55
	v_writelane_b32 v254, s74, 56
	s_nop 1
	v_writelane_b32 v254, s75, 57
	s_branch .LBB0_291

.LBB0_291:
	v_writelane_b32 v254, s0, 58
	s_lshl_b32 s8, s0, 2
	v_readlane_b32 s0, v251, 60
	s_add_i32 s8, s8, s0
	s_mov_b64 s[2:3], exec
	v_readlane_b32 s0, v251, 61
	v_readlane_b32 s1, v251, 62
	s_and_b64 s[0:1], s[2:3], s[0:1]
	s_mov_b64 exec, s[0:1]
	s_cbranch_execz .LBB0_304
	v_or_b32_e32 v0, s8, v191
	v_lshlrev_b64 v[2:3], 10, v[0:1]
	v_lshl_add_u64 v[2:3], v[174:175], 0, v[2:3]
	v_or_b32_e32 v0, s8, v192
	global_load_dwordx4 v[18:21], v[2:3], off
	global_load_dwordx4 v[22:25], v[2:3], off offset:32
	global_load_dwordx4 v[26:29], v[2:3], off offset:64
	global_load_dwordx4 v[30:33], v[2:3], off offset:96
	v_or_b32_e32 v2, 1, v0
	v_ashrrev_i32_e32 v3, 31, v2
	v_readlane_b32 s0, v252, 41
	v_lshlrev_b64 v[2:3], 5, v[2:3]
	v_readlane_b32 s1, v252, 42
	s_mov_b32 s9, 4
	s_mov_b64 s[4:5], 0
	v_lshl_add_u64 v[6:7], s[0:1], 0, v[2:3]
	v_lshlrev_b64 v[2:3], 5, v[0:1]
	v_lshl_add_u64 v[2:3], s[0:1], 0, v[2:3]
	global_load_dwordx4 v[34:37], v[2:3], off
	global_load_dwordx4 v[38:41], v[2:3], off offset:16
	global_load_dwordx4 v[166:169], v[186:187], off offset:1024
	s_nop 0
	global_load_dwordx4 v[2:5], v[186:187], off
	global_load_dwordx4 v[162:165], v[186:187], off offset:3072
	global_load_dwordx4 v[170:173], v[186:187], off offset:2048
	global_load_dwordx4 v[150:153], v[184:185], off offset:1024
	global_load_dwordx4 v[154:157], v[184:185], off
	global_load_dwordx4 v[146:149], v[184:185], off offset:3072
	global_load_dwordx4 v[158:161], v[184:185], off offset:2048
	global_load_dwordx4 v[134:137], v[182:183], off offset:1024
	global_load_dwordx4 v[138:141], v[182:183], off
	global_load_dwordx4 v[130:133], v[182:183], off offset:3072
	global_load_dwordx4 v[142:145], v[182:183], off offset:2048
	global_load_dwordx4 v[118:121], v[180:181], off offset:1024
	global_load_dwordx4 v[122:125], v[180:181], off
	global_load_dwordx4 v[114:117], v[180:181], off offset:3072
	global_load_dwordx4 v[126:129], v[180:181], off offset:2048
	global_load_dwordx4 v[42:45], v[6:7], off
	global_load_dwordx4 v[46:49], v[6:7], off offset:16
	v_mov_b32_e32 v197, v189
	v_mov_b32_e32 v0, v195
	s_waitcnt vmcnt(0)
	v_mov_b64_e32 v[54:55], v[166:167]
	v_mov_b64_e32 v[52:53], v[4:5]
	v_mov_b64_e32 v[62:63], v[162:163]
	v_mov_b64_e32 v[58:59], v[170:171]
	v_mov_b64_e32 v[70:71], v[150:151]
	v_mov_b64_e32 v[66:67], v[154:155]
	v_mov_b64_e32 v[78:79], v[146:147]
	v_mov_b64_e32 v[74:75], v[158:159]
	v_mov_b64_e32 v[86:87], v[134:135]
	v_mov_b64_e32 v[82:83], v[138:139]
	v_mov_b64_e32 v[94:95], v[130:131]
	v_mov_b64_e32 v[90:91], v[142:143]
	v_mov_b64_e32 v[102:103], v[118:119]
	v_mov_b64_e32 v[98:99], v[122:123]
	v_mov_b64_e32 v[110:111], v[114:115]
	v_mov_b64_e32 v[106:107], v[126:127]
	v_mov_b64_e32 v[50:51], v[2:3]
	v_mov_b64_e32 v[56:57], v[168:169]
	v_mov_b64_e32 v[60:61], v[172:173]
	v_mov_b64_e32 v[64:65], v[164:165]
	v_mov_b64_e32 v[68:69], v[156:157]
	v_mov_b64_e32 v[72:73], v[152:153]
	v_mov_b64_e32 v[76:77], v[160:161]
	v_mov_b64_e32 v[80:81], v[148:149]
	v_mov_b64_e32 v[84:85], v[140:141]
	v_mov_b64_e32 v[88:89], v[136:137]
	v_mov_b64_e32 v[92:93], v[144:145]
	v_mov_b64_e32 v[96:97], v[132:133]
	v_mov_b64_e32 v[100:101], v[124:125]
	v_mov_b64_e32 v[104:105], v[120:121]
	v_mov_b64_e32 v[108:109], v[128:129]
	v_mov_b64_e32 v[112:113], v[116:117]
	s_branch .LBB0_294

.LBB0_294:
	v_cmp_lt_i32_e64 s[0:1], s9, v193
	v_cmp_ge_i32_e32 vcc, s9, v193
	v_add_u32_e32 v196, 16, v197
	s_and_saveexec_b64 s[6:7], s[0:1]
	s_cbranch_execz .LBB0_296
	v_add_u32_e32 v6, 16, v197
	v_min_i32_e32 v6, s95, v6
	v_lshl_or_b32 v6, v6, 8, v190
	v_ashrrev_i32_e32 v7, 31, v6
	v_lshlrev_b64 v[6:7], 4, v[6:7]
	v_lshl_add_u64 v[6:7], v[176:177], 0, v[6:7]
	global_load_dwordx4 v[50:53], v[6:7], off
	global_load_dwordx4 v[54:57], v[6:7], off offset:1024
	global_load_dwordx4 v[58:61], v[6:7], off offset:2048
	global_load_dwordx4 v[62:65], v[6:7], off offset:3072
	v_add_u32_e32 v6, 20, v197
	v_min_i32_e32 v6, s95, v6
	v_lshl_or_b32 v6, v6, 8, v190
	v_ashrrev_i32_e32 v7, 31, v6
	v_lshlrev_b64 v[6:7], 4, v[6:7]
	v_lshl_add_u64 v[6:7], v[176:177], 0, v[6:7]
	global_load_dwordx4 v[66:69], v[6:7], off
	global_load_dwordx4 v[70:73], v[6:7], off offset:1024
	global_load_dwordx4 v[74:77], v[6:7], off offset:2048
	global_load_dwordx4 v[78:81], v[6:7], off offset:3072
	v_add_u32_e32 v6, 24, v197
	v_min_i32_e32 v6, s95, v6
	v_lshl_or_b32 v6, v6, 8, v190
	v_ashrrev_i32_e32 v7, 31, v6
	v_lshlrev_b64 v[6:7], 4, v[6:7]
	v_lshl_add_u64 v[6:7], v[176:177], 0, v[6:7]
	global_load_dwordx4 v[82:85], v[6:7], off
	global_load_dwordx4 v[86:89], v[6:7], off offset:1024
	global_load_dwordx4 v[90:93], v[6:7], off offset:2048
	global_load_dwordx4 v[94:97], v[6:7], off offset:3072
	v_add_u32_e32 v6, 28, v197
	v_min_i32_e32 v6, s95, v6
	v_lshl_or_b32 v6, v6, 8, v190
	v_ashrrev_i32_e32 v7, 31, v6
	v_lshlrev_b64 v[6:7], 4, v[6:7]
	v_lshl_add_u64 v[6:7], v[176:177], 0, v[6:7]
	global_load_dwordx4 v[98:101], v[6:7], off
	global_load_dwordx4 v[102:105], v[6:7], off offset:1024
	global_load_dwordx4 v[106:109], v[6:7], off offset:2048
	global_load_dwordx4 v[110:113], v[6:7], off offset:3072
